# grid barrier: non-leader workgroups poll the cross-XCD release generation directly (one release hop removed)
# speedup vs baseline: 1.0039x; 1.0039x over previous
; __device__ __forceinline__ unsigned xb_ld(GAS unsigned* p)              { return __hip_atomic_load(p, __ATOMIC_RELAXED, __HIP_MEMORY_SCOPE_AGENT); }
; __device__ __forceinline__ unsigned xb_add(GAS unsigned* p, unsigned v) { return __hip_atomic_fetch_add(p, v, __ATOMIC_RELAXED, __HIP_MEMORY_SCOPE_AGENT); }
; #define XB_SPIN(cond, bar) do { unsigned _sp = 0; while (cond) { __builtin_amdgcn_s_sleep(1); \
;     if ((++_sp & 255u) == 0u) { if (xb_ld(&(bar)[XB_TMO])) break; if (_sp > XB_SPIN_CAP) { xb_add(&(bar)[XB_TMO], 1u); break; } } } } while (0)
; __device__ __forceinline__ void xcd_barrier(const XcdBarrier& b) {
;     ...
;         const unsigned old = xb_add(&bar[XB_XSUB(b.x)], 1u);
;         const unsigned gen = old / nloc;
;         if (old + 1u == (gen + 1u) * nloc) {
;             __builtin_amdgcn_fence(__ATOMIC_RELEASE, "agent");
;             asm volatile("s_waitcnt vmcnt(0)" ::: "memory");
;             const unsigned og = xb_add(&bar[XB_TOP], 1u);
;             const unsigned tg = og / nx;
;             if (og + 1u == (tg + 1u) * nx) xb_add(&bar[XB_TOPGEN], 1u);
;             else XB_SPIN(xb_ld(&bar[XB_TOPGEN]) == tg, bar);
;             __builtin_amdgcn_fence(__ATOMIC_ACQUIRE, "agent");
;             xb_add(&bar[XB_XGEN(b.x)], 1u);
;             asm volatile("s_waitcnt vmcnt(0)" ::: "memory");
;         } else {
;             XB_SPIN(xb_ld(&bar[XB_XGEN(b.x)]) == gen, bar);
;             __builtin_amdgcn_fence(__ATOMIC_ACQUIRE, "agent");
;             asm volatile("s_waitcnt vmcnt(0)" ::: "memory");
;         }
.LBB0_105:
	s_or_b64 exec, exec, s[10:11]
	v_cvt_f32_u32_e32 v5, v3
	s_waitcnt vmcnt(0)
	v_readfirstlane_b32 s8, v4
	v_sub_u32_e32 v4, 0, v3
	v_rcp_iflag_f32_e32 v5, v5
	v_add_u32_e32 v6, s8, v0
	v_mul_f32_e32 v5, 0x4f7ffffe, v5
	v_cvt_u32_f32_e32 v5, v5
	v_mul_lo_u32 v0, v4, v5
	v_mul_hi_u32 v0, v5, v0
	v_add_u32_e32 v0, v5, v0
	v_mul_hi_u32 v0, v6, v0
	v_mul_lo_u32 v4, v0, v3
	v_sub_u32_e32 v4, v6, v4
	v_add_u32_e32 v5, 1, v0
	v_cmp_ge_u32_e32 vcc, v4, v3
	s_nop 1
	v_cndmask_b32_e32 v0, v0, v5, vcc
	v_sub_u32_e32 v5, v4, v3
	v_cndmask_b32_e32 v4, v4, v5, vcc
	v_add_u32_e32 v5, 1, v0
	v_cmp_ge_u32_e32 vcc, v4, v3
	v_add_u32_e32 v4, 1, v6
	s_nop 0
	v_cndmask_b32_e32 v0, v0, v5, vcc
	v_mul_lo_u32 v5, v3, v0
	v_add_u32_e32 v3, v5, v3
	v_cmp_ne_u32_e32 vcc, v4, v3
	s_and_saveexec_b64 s[8:9], vcc
	s_xor_b64 s[8:9], exec, s[8:9]
	s_cbranch_execz .LBB0_119
	s_waitcnt lgkmcnt(0)
	s_add_u32 s14, s4, 0x4500
	s_addc_u32 s15, s5, 0
	global_load_dword v2, v1, s[14:15] sc1
	s_waitcnt vmcnt(0)
	v_cmp_eq_u32_e32 vcc, v2, v0
	s_and_saveexec_b64 s[10:11], vcc
	s_cbranch_execz .LBB0_118
	s_add_u32 s12, s4, 0x1200
	s_addc_u32 s13, s5, 0
	s_mov_b32 s26, 1
	s_mov_b64 s[16:17], 0
	s_branch .LBB0_109

; __device__ __forceinline__ unsigned xb_ld(GAS unsigned* p)              { return __hip_atomic_load(p, __ATOMIC_RELAXED, __HIP_MEMORY_SCOPE_AGENT); }
; __device__ __forceinline__ unsigned xb_add(GAS unsigned* p, unsigned v) { return __hip_atomic_fetch_add(p, v, __ATOMIC_RELAXED, __HIP_MEMORY_SCOPE_AGENT); }
; #define XB_SPIN(cond, bar) do { unsigned _sp = 0; while (cond) { __builtin_amdgcn_s_sleep(1); \
;     if ((++_sp & 255u) == 0u) { if (xb_ld(&(bar)[XB_TMO])) break; if (_sp > XB_SPIN_CAP) { xb_add(&(bar)[XB_TMO], 1u); break; } } } } while (0)
; __device__ __forceinline__ void xcd_barrier(const XcdBarrier& b) {
;     ...
;         const unsigned old = xb_add(&bar[XB_XSUB(b.x)], 1u);
;         const unsigned gen = old / nloc;
;         if (old + 1u == (gen + 1u) * nloc) {
;             __builtin_amdgcn_fence(__ATOMIC_RELEASE, "agent");
;             asm volatile("s_waitcnt vmcnt(0)" ::: "memory");
;             const unsigned og = xb_add(&bar[XB_TOP], 1u);
;             const unsigned tg = og / nx;
;             if (og + 1u == (tg + 1u) * nx) xb_add(&bar[XB_TOPGEN], 1u);
;             else XB_SPIN(xb_ld(&bar[XB_TOPGEN]) == tg, bar);
;             __builtin_amdgcn_fence(__ATOMIC_ACQUIRE, "agent");
;             xb_add(&bar[XB_XGEN(b.x)], 1u);
;             asm volatile("s_waitcnt vmcnt(0)" ::: "memory");
;         } else {
;             XB_SPIN(xb_ld(&bar[XB_XGEN(b.x)]) == gen, bar);
;             __builtin_amdgcn_fence(__ATOMIC_ACQUIRE, "agent");
;             asm volatile("s_waitcnt vmcnt(0)" ::: "memory");
;         }
.LBB0_274:
	s_or_b64 exec, exec, s[8:9]
	v_cvt_f32_u32_e32 v5, v3
	s_waitcnt vmcnt(0)
	v_readfirstlane_b32 s6, v4
	v_sub_u32_e32 v4, 0, v3
	v_rcp_iflag_f32_e32 v5, v5
	v_add_u32_e32 v6, s6, v0
	v_mul_f32_e32 v5, 0x4f7ffffe, v5
	v_cvt_u32_f32_e32 v5, v5
	v_mul_lo_u32 v0, v4, v5
	v_mul_hi_u32 v0, v5, v0
	v_add_u32_e32 v0, v5, v0
	v_mul_hi_u32 v0, v6, v0
	v_mul_lo_u32 v4, v0, v3
	v_sub_u32_e32 v4, v6, v4
	v_add_u32_e32 v5, 1, v0
	v_cmp_ge_u32_e32 vcc, v4, v3
	s_nop 1
	v_cndmask_b32_e32 v0, v0, v5, vcc
	v_sub_u32_e32 v5, v4, v3
	v_cndmask_b32_e32 v4, v4, v5, vcc
	v_add_u32_e32 v5, 1, v0
	v_cmp_ge_u32_e32 vcc, v4, v3
	v_add_u32_e32 v4, 1, v6
	s_nop 0
	v_cndmask_b32_e32 v0, v0, v5, vcc
	v_mul_lo_u32 v5, v3, v0
	v_add_u32_e32 v3, v5, v3
	v_cmp_ne_u32_e32 vcc, v4, v3
	s_and_saveexec_b64 s[6:7], vcc
	s_xor_b64 s[6:7], exec, s[6:7]
	s_cbranch_execz .LBB0_288
	s_waitcnt lgkmcnt(0)
	s_add_u32 s12, s2, 0x4500
	s_addc_u32 s13, s3, 0
	global_load_dword v2, v1, s[12:13] sc1
	s_waitcnt vmcnt(0)
	v_cmp_eq_u32_e32 vcc, v2, v0
	s_and_saveexec_b64 s[8:9], vcc
	s_cbranch_execz .LBB0_287
	s_add_u32 s10, s2, 0x1200
	s_addc_u32 s11, s3, 0
	s_mov_b32 s24, 1
	s_mov_b64 s[14:15], 0
	s_branch .LBB0_278

; __device__ __forceinline__ unsigned xb_ld(GAS unsigned* p)              { return __hip_atomic_load(p, __ATOMIC_RELAXED, __HIP_MEMORY_SCOPE_AGENT); }
; __device__ __forceinline__ unsigned xb_add(GAS unsigned* p, unsigned v) { return __hip_atomic_fetch_add(p, v, __ATOMIC_RELAXED, __HIP_MEMORY_SCOPE_AGENT); }
; #define XB_SPIN(cond, bar) do { unsigned _sp = 0; while (cond) { __builtin_amdgcn_s_sleep(1); \
;     if ((++_sp & 255u) == 0u) { if (xb_ld(&(bar)[XB_TMO])) break; if (_sp > XB_SPIN_CAP) { xb_add(&(bar)[XB_TMO], 1u); break; } } } } while (0)
; __device__ __forceinline__ void xcd_barrier(const XcdBarrier& b) {
;     ...
;         const unsigned old = xb_add(&bar[XB_XSUB(b.x)], 1u);
;         const unsigned gen = old / nloc;
;         if (old + 1u == (gen + 1u) * nloc) {
;             __builtin_amdgcn_fence(__ATOMIC_RELEASE, "agent");
;             asm volatile("s_waitcnt vmcnt(0)" ::: "memory");
;             const unsigned og = xb_add(&bar[XB_TOP], 1u);
;             const unsigned tg = og / nx;
;             if (og + 1u == (tg + 1u) * nx) xb_add(&bar[XB_TOPGEN], 1u);
;             else XB_SPIN(xb_ld(&bar[XB_TOPGEN]) == tg, bar);
;             __builtin_amdgcn_fence(__ATOMIC_ACQUIRE, "agent");
;             xb_add(&bar[XB_XGEN(b.x)], 1u);
;             asm volatile("s_waitcnt vmcnt(0)" ::: "memory");
;         } else {
;             XB_SPIN(xb_ld(&bar[XB_XGEN(b.x)]) == gen, bar);
;             __builtin_amdgcn_fence(__ATOMIC_ACQUIRE, "agent");
;             asm volatile("s_waitcnt vmcnt(0)" ::: "memory");
;         }
.LBB0_913:
	s_or_b64 exec, exec, s[8:9]
	v_cvt_f32_u32_e32 v5, v3
	s_waitcnt vmcnt(0)
	v_readfirstlane_b32 s6, v4
	v_sub_u32_e32 v4, 0, v3
	v_rcp_iflag_f32_e32 v5, v5
	v_add_u32_e32 v6, s6, v0
	v_mul_f32_e32 v5, 0x4f7ffffe, v5
	v_cvt_u32_f32_e32 v5, v5
	v_mul_lo_u32 v0, v4, v5
	v_mul_hi_u32 v0, v5, v0
	v_add_u32_e32 v0, v5, v0
	v_mul_hi_u32 v0, v6, v0
	v_mul_lo_u32 v4, v0, v3
	v_sub_u32_e32 v4, v6, v4
	v_add_u32_e32 v5, 1, v0
	v_cmp_ge_u32_e32 vcc, v4, v3
	s_nop 1
	v_cndmask_b32_e32 v0, v0, v5, vcc
	v_sub_u32_e32 v5, v4, v3
	v_cndmask_b32_e32 v4, v4, v5, vcc
	v_add_u32_e32 v5, 1, v0
	v_cmp_ge_u32_e32 vcc, v4, v3
	v_add_u32_e32 v4, 1, v6
	s_nop 0
	v_cndmask_b32_e32 v0, v0, v5, vcc
	v_mul_lo_u32 v5, v3, v0
	v_add_u32_e32 v3, v5, v3
	v_cmp_ne_u32_e32 vcc, v4, v3
	s_and_saveexec_b64 s[6:7], vcc
	s_xor_b64 s[6:7], exec, s[6:7]
	v_readlane_b32 s30, v254, 32
	s_cbranch_execz .LBB0_927
	s_waitcnt lgkmcnt(0)
	s_add_u32 s12, s2, 0x4500
	s_addc_u32 s13, s3, 0
	global_load_dword v2, v1, s[12:13] sc1
	s_waitcnt vmcnt(0)
	v_cmp_eq_u32_e32 vcc, v2, v0
	s_and_saveexec_b64 s[8:9], vcc
	s_cbranch_execz .LBB0_926
	s_add_u32 s10, s2, 0x1200
	s_addc_u32 s11, s3, 0
	s_mov_b32 s24, 1
	s_mov_b64 s[14:15], 0
	s_branch .LBB0_917
